# in-proj tile balance: the 16 workgroups that receive a second (ctx) ret-k tile swap their regular ret-k tile with a plain tile of a 9-tile workgroup
# speedup vs baseline: 1.0010x; 1.0010x over previous
.LBB0_138:
	s_cmpk_gt_i32 s65, 0x8ff
	s_cselect_b64 s[28:29], -1, 0
	s_cmpk_lt_i32 s65, 0x900
	s_cselect_b64 s[34:35], -1, 0
	s_mov_b64 s[4:5], -1
	s_and_b64 vcc, exec, s[28:29]
	s_cbranch_vccnz .LBB0_140
	s_add_i32 s5, s65, 0x80
	s_sub_u32 s4, s65, 0x620
	s_cmp_lt_u32 s4, 16
	s_cselect_b32 s26, s5, s65
	s_add_i32 s5, s65, 0xffffff80
	s_sub_u32 s4, s65, 0x6a0
	s_cmp_lt_u32 s4, 16
	s_cselect_b32 s26, s5, s26
	s_mul_hi_i32 s4, s26, 0x38e38e39
	s_lshr_b32 s5, s4, 31
	s_ashr_i32 s4, s4, 6
	s_add_i32 s4, s4, s5
	s_mul_i32 s5, s4, 0x120
	s_sub_i32 s5, s26, s5
	s_bfe_u32 s6, s5, 0x4001b
	s_add_i32 s6, s5, s6
	s_sext_i32_i16 s26, s6
	s_and_b32 s6, s6, 0xfff0
	s_sub_i32 s5, s5, s6
	s_lshl_b32 s4, s4, 4
	s_sext_i32_i16 s5, s5
	s_ashr_i32 s26, s26, 4
	s_add_i32 s6, s4, s5
	s_mov_b64 s[4:5], 0
